# accumulator zeroing at every GEMM tile header: 127 v_mov_b32 replaced by 64 v_mov_b64 (seven tile loops); on v071
# speedup vs baseline: 1.0205x; 1.0043x over previous
.LBB0_177:
	s_ashr_i32 s45, s44, 31
	v_cmp_lt_i64_e32 vcc, s[46:47], v[144:145]
	s_lshl_b64 s[46:47], s[44:45], 19
	s_add_u32 s46, s68, s46
	s_addc_u32 s47, s69, s47
	s_and_b64 s[48:49], vcc, exec
	s_cselect_b32 s11, s47, s51
	s_cselect_b32 s13, s46, s50
	s_ashr_i32 s43, s42, 31
	s_lshl_b64 s[48:49], s[42:43], 19
	s_add_u32 s48, s26, s48
	s_addc_u32 s49, s27, s49
	s_and_b64 s[54:55], vcc, exec
	s_cselect_b32 s17, s49, s53
	s_cselect_b32 s43, s48, s52
	s_add_u32 s50, s50, 0x40080
	s_addc_u32 s51, s51, 0
	s_add_u32 s45, s52, 0x100
	v_mov_b32_e32 v0, 0
	s_addc_u32 s91, s53, 0
	s_mov_b32 s92, -2
	v_mov_b32_e32 v1, v0
	v_mov_b32_e32 v2, v0
	v_mov_b32_e32 v3, v0
	v_mov_b32_e32 v4, v0
	v_mov_b32_e32 v5, v0
	v_mov_b32_e32 v6, v0
	v_mov_b32_e32 v7, v0
	v_mov_b32_e32 v16, v0
	v_mov_b32_e32 v17, v0
	s_waitcnt lgkmcnt(0)
	v_mov_b64_e32 v[8:9], 0
	v_mov_b64_e32 v[10:11], 0
	v_mov_b64_e32 v[12:13], 0
	v_mov_b64_e32 v[14:15], 0
	v_mov_b64_e32 v[18:19], 0
	v_mov_b64_e32 v[20:21], 0
	v_mov_b64_e32 v[22:23], 0
	v_mov_b64_e32 v[24:25], 0
	v_mov_b64_e32 v[26:27], 0
	v_mov_b64_e32 v[28:29], 0
	v_mov_b64_e32 v[30:31], 0
	v_mov_b64_e32 v[32:33], 0
	v_mov_b64_e32 v[34:35], 0
	v_mov_b64_e32 v[36:37], 0
	v_mov_b64_e32 v[38:39], 0
	v_mov_b64_e32 v[40:41], 0
	v_mov_b64_e32 v[42:43], 0
	v_mov_b64_e32 v[44:45], 0
	v_mov_b64_e32 v[46:47], 0
	v_mov_b64_e32 v[48:49], 0
	v_mov_b64_e32 v[50:51], 0
	v_mov_b64_e32 v[52:53], 0
	v_mov_b64_e32 v[54:55], 0
	v_mov_b64_e32 v[56:57], 0
	v_mov_b64_e32 v[58:59], 0
	v_mov_b64_e32 v[60:61], 0
	v_mov_b64_e32 v[62:63], 0
	v_mov_b64_e32 v[64:65], 0
	v_mov_b64_e32 v[66:67], 0
	v_mov_b64_e32 v[68:69], 0
	v_mov_b64_e32 v[70:71], 0
	v_mov_b64_e32 v[72:73], 0
	v_mov_b64_e32 v[74:75], 0
	v_mov_b64_e32 v[76:77], 0
	v_mov_b64_e32 v[78:79], 0
	v_mov_b64_e32 v[80:81], 0
	v_mov_b64_e32 v[82:83], 0
	v_mov_b64_e32 v[84:85], 0
	v_mov_b64_e32 v[86:87], 0
	v_mov_b64_e32 v[88:89], 0
	v_mov_b64_e32 v[90:91], 0
	v_mov_b64_e32 v[92:93], 0
	v_mov_b64_e32 v[94:95], 0
	v_mov_b64_e32 v[96:97], 0
	v_mov_b64_e32 v[98:99], 0
	v_mov_b64_e32 v[100:101], 0
	v_mov_b64_e32 v[102:103], 0
	v_mov_b64_e32 v[104:105], 0
	v_mov_b64_e32 v[106:107], 0
	v_mov_b64_e32 v[108:109], 0
	v_mov_b64_e32 v[110:111], 0
	v_mov_b64_e32 v[112:113], 0
	v_mov_b64_e32 v[114:115], 0
	v_mov_b64_e32 v[116:117], 0
	v_mov_b64_e32 v[118:119], 0
	v_mov_b64_e32 v[120:121], 0
	v_mov_b64_e32 v[122:123], 0
	v_mov_b64_e32 v[124:125], 0
	v_mov_b64_e32 v[126:127], 0

.LBB0_341:
	s_ashr_i32 s9, s8, 31
	v_cmp_lt_i64_e64 s[48:49], s[10:11], 64
	s_lshl_b64 s[10:11], s[8:9], 19
	s_add_u32 s10, s82, s10
	s_addc_u32 s11, s83, s11
	s_and_b64 s[12:13], s[48:49], exec
	s_cselect_b32 s9, s11, s45
	s_cselect_b32 s63, s10, s44
	s_ashr_i32 s7, s6, 31
	s_lshl_b64 s[12:13], s[6:7], 19
	s_add_u32 s12, s80, s12
	s_addc_u32 s13, s81, s13
	s_and_b64 s[48:49], s[48:49], exec
	s_cselect_b32 s7, s13, s47
	s_cselect_b32 s64, s12, s46
	s_add_u32 s44, s44, 0x40080
	s_addc_u32 s45, s45, 0
	s_add_u32 s65, s46, 0x100
	v_mov_b32_e32 v0, 0
	s_addc_u32 s66, s47, 0
	s_mov_b32 s67, -2
	v_mov_b64_e32 v[0:1], 0
	v_mov_b64_e32 v[2:3], 0
	v_mov_b64_e32 v[4:5], 0
	v_mov_b64_e32 v[6:7], 0
	v_mov_b64_e32 v[8:9], 0
	v_mov_b64_e32 v[10:11], 0
	v_mov_b64_e32 v[12:13], 0
	v_mov_b64_e32 v[14:15], 0
	v_mov_b64_e32 v[16:17], 0
	v_mov_b64_e32 v[18:19], 0
	v_mov_b64_e32 v[20:21], 0
	v_mov_b64_e32 v[22:23], 0
	v_mov_b64_e32 v[24:25], 0
	v_mov_b64_e32 v[26:27], 0
	v_mov_b64_e32 v[28:29], 0
	v_mov_b64_e32 v[30:31], 0
	v_mov_b64_e32 v[32:33], 0
	v_mov_b64_e32 v[34:35], 0
	v_mov_b64_e32 v[36:37], 0
	v_mov_b64_e32 v[38:39], 0
	v_mov_b64_e32 v[40:41], 0
	v_mov_b64_e32 v[42:43], 0
	v_mov_b64_e32 v[44:45], 0
	v_mov_b64_e32 v[46:47], 0
	v_mov_b64_e32 v[48:49], 0
	v_mov_b64_e32 v[50:51], 0
	v_mov_b64_e32 v[52:53], 0
	v_mov_b64_e32 v[54:55], 0
	v_mov_b64_e32 v[56:57], 0
	v_mov_b64_e32 v[58:59], 0
	v_mov_b64_e32 v[60:61], 0
	v_mov_b64_e32 v[62:63], 0
	v_mov_b64_e32 v[64:65], 0
	v_mov_b64_e32 v[66:67], 0
	v_mov_b64_e32 v[68:69], 0
	v_mov_b64_e32 v[70:71], 0
	v_mov_b64_e32 v[72:73], 0
	v_mov_b64_e32 v[74:75], 0
	v_mov_b64_e32 v[76:77], 0
	v_mov_b64_e32 v[78:79], 0
	v_mov_b64_e32 v[80:81], 0
	v_mov_b64_e32 v[82:83], 0
	v_mov_b64_e32 v[84:85], 0
	v_mov_b64_e32 v[86:87], 0
	v_mov_b64_e32 v[88:89], 0
	v_mov_b64_e32 v[90:91], 0
	v_mov_b64_e32 v[92:93], 0
	v_mov_b64_e32 v[94:95], 0
	v_mov_b64_e32 v[96:97], 0
	v_mov_b64_e32 v[98:99], 0
	v_mov_b64_e32 v[100:101], 0
	v_mov_b64_e32 v[102:103], 0
	v_mov_b64_e32 v[104:105], 0
	v_mov_b64_e32 v[106:107], 0
	v_mov_b64_e32 v[108:109], 0
	v_mov_b64_e32 v[110:111], 0
	v_mov_b64_e32 v[112:113], 0
	v_mov_b64_e32 v[114:115], 0
	v_mov_b64_e32 v[116:117], 0
	v_mov_b64_e32 v[118:119], 0
	v_mov_b64_e32 v[120:121], 0
	v_mov_b64_e32 v[122:123], 0
	v_mov_b64_e32 v[124:125], 0
	v_mov_b64_e32 v[126:127], 0

.LBB0_739:
	s_ashr_i32 s57, s56, 31
	v_cmp_lt_i64_e32 vcc, s[58:59], v[208:209]
	s_lshl_b64 s[58:59], s[56:57], 19
	s_add_u32 s58, s68, s58
	s_addc_u32 s59, s69, s59
	s_and_b64 s[60:61], vcc, exec
	s_cselect_b32 s9, s59, s11
	s_cselect_b32 s13, s58, s10
	s_ashr_i32 s55, s54, 31
	s_lshl_b64 s[60:61], s[54:55], 19
	s_add_u32 s60, s76, s60
	s_addc_u32 s61, s77, s61
	s_and_b64 s[64:65], vcc, exec
	s_cselect_b32 s17, s61, s63
	s_cselect_b32 s44, s60, s62
	s_add_u32 s10, s10, 0x40080
	s_addc_u32 s11, s11, 0
	s_add_u32 s55, s62, 0x100
	v_mov_b32_e32 v0, 0
	s_addc_u32 s57, s63, 0
	s_mov_b32 s92, -2
	s_waitcnt lgkmcnt(0)
	v_mov_b64_e32 v[0:1], 0
	v_mov_b64_e32 v[2:3], 0
	v_mov_b64_e32 v[4:5], 0
	v_mov_b64_e32 v[6:7], 0
	v_mov_b64_e32 v[8:9], 0
	v_mov_b64_e32 v[10:11], 0
	v_mov_b64_e32 v[12:13], 0
	v_mov_b64_e32 v[14:15], 0
	v_mov_b64_e32 v[16:17], 0
	v_mov_b64_e32 v[18:19], 0
	v_mov_b64_e32 v[20:21], 0
	v_mov_b64_e32 v[22:23], 0
	v_mov_b64_e32 v[24:25], 0
	v_mov_b64_e32 v[26:27], 0
	v_mov_b64_e32 v[28:29], 0
	v_mov_b64_e32 v[30:31], 0
	v_mov_b64_e32 v[32:33], 0
	v_mov_b64_e32 v[34:35], 0
	v_mov_b64_e32 v[36:37], 0
	v_mov_b64_e32 v[38:39], 0
	v_mov_b64_e32 v[40:41], 0
	v_mov_b64_e32 v[42:43], 0
	v_mov_b64_e32 v[44:45], 0
	v_mov_b64_e32 v[46:47], 0
	v_mov_b64_e32 v[48:49], 0
	v_mov_b64_e32 v[50:51], 0
	v_mov_b64_e32 v[52:53], 0
	v_mov_b64_e32 v[54:55], 0
	v_mov_b64_e32 v[56:57], 0
	v_mov_b64_e32 v[58:59], 0
	v_mov_b64_e32 v[60:61], 0
	v_mov_b64_e32 v[62:63], 0
	v_mov_b64_e32 v[72:73], 0
	v_mov_b64_e32 v[74:75], 0
	v_mov_b64_e32 v[76:77], 0
	v_mov_b64_e32 v[78:79], 0
	v_mov_b64_e32 v[80:81], 0
	v_mov_b64_e32 v[82:83], 0
	v_mov_b64_e32 v[88:89], 0
	v_mov_b64_e32 v[90:91], 0
	v_mov_b64_e32 v[96:97], 0
	v_mov_b64_e32 v[98:99], 0
	v_mov_b64_e32 v[100:101], 0
	v_mov_b64_e32 v[102:103], 0
	v_mov_b64_e32 v[104:105], 0
	v_mov_b64_e32 v[106:107], 0
	v_mov_b64_e32 v[108:109], 0
	v_mov_b64_e32 v[110:111], 0
	v_mov_b64_e32 v[112:113], 0
	v_mov_b64_e32 v[114:115], 0
	v_mov_b64_e32 v[116:117], 0
	v_mov_b64_e32 v[118:119], 0
	v_mov_b64_e32 v[120:121], 0
	v_mov_b64_e32 v[122:123], 0
	v_mov_b64_e32 v[124:125], 0
	v_mov_b64_e32 v[126:127], 0
	v_mov_b64_e32 v[128:129], 0
	v_mov_b64_e32 v[130:131], 0
	v_mov_b64_e32 v[132:133], 0
	v_mov_b64_e32 v[134:135], 0
	v_mov_b64_e32 v[136:137], 0
	v_mov_b64_e32 v[138:139], 0
	v_mov_b64_e32 v[140:141], 0
	v_mov_b64_e32 v[142:143], 0

.LBB0_903:
	s_ashr_i32 s45, s44, 31
	v_cmp_lt_i64_e32 vcc, s[0:1], v[142:143]
	s_lshl_b64 s[0:1], s[44:45], 19
	s_add_u32 s46, s42, s0
	s_addc_u32 s47, s43, s1
	s_and_b64 s[0:1], vcc, exec
	s_cselect_b32 s7, s47, s53
	s_cselect_b32 s45, s46, s52
	s_ashr_i32 s37, s36, 31
	s_lshl_b64 s[0:1], s[36:37], 19
	s_add_u32 s48, s74, s0
	s_addc_u32 s49, s75, s1
	s_and_b64 s[0:1], vcc, exec
	s_cselect_b32 s37, s49, s51
	s_cselect_b32 s67, s48, s50
	s_add_u32 s0, s52, 0x40080
	s_addc_u32 s1, s53, 0
	s_add_u32 s76, s50, 0x100
	v_mov_b32_e32 v0, 0
	s_addc_u32 s77, s51, 0
	s_mov_b32 s78, -2
	v_mov_b64_e32 v[0:1], 0
	v_mov_b64_e32 v[2:3], 0
	v_mov_b64_e32 v[4:5], 0
	v_mov_b64_e32 v[6:7], 0
	v_mov_b64_e32 v[8:9], 0
	v_mov_b64_e32 v[10:11], 0
	v_mov_b64_e32 v[12:13], 0
	v_mov_b64_e32 v[14:15], 0
	v_mov_b64_e32 v[16:17], 0
	v_mov_b64_e32 v[18:19], 0
	v_mov_b64_e32 v[20:21], 0
	v_mov_b64_e32 v[22:23], 0
	v_mov_b64_e32 v[24:25], 0
	v_mov_b64_e32 v[26:27], 0
	v_mov_b64_e32 v[28:29], 0
	v_mov_b64_e32 v[30:31], 0
	v_mov_b64_e32 v[32:33], 0
	v_mov_b64_e32 v[34:35], 0
	v_mov_b64_e32 v[36:37], 0
	v_mov_b64_e32 v[38:39], 0
	v_mov_b64_e32 v[40:41], 0
	v_mov_b64_e32 v[42:43], 0
	v_mov_b64_e32 v[44:45], 0
	v_mov_b64_e32 v[46:47], 0
	v_mov_b64_e32 v[48:49], 0
	v_mov_b64_e32 v[50:51], 0
	v_mov_b64_e32 v[52:53], 0
	v_mov_b64_e32 v[54:55], 0
	v_mov_b64_e32 v[56:57], 0
	v_mov_b64_e32 v[58:59], 0
	v_mov_b64_e32 v[60:61], 0
	v_mov_b64_e32 v[62:63], 0
	v_mov_b64_e32 v[64:65], 0
	v_mov_b64_e32 v[66:67], 0
	v_mov_b64_e32 v[68:69], 0
	v_mov_b64_e32 v[70:71], 0
	v_mov_b64_e32 v[72:73], 0
	v_mov_b64_e32 v[74:75], 0
	v_mov_b64_e32 v[76:77], 0
	v_mov_b64_e32 v[78:79], 0
	v_mov_b64_e32 v[80:81], 0
	v_mov_b64_e32 v[82:83], 0
	v_mov_b64_e32 v[84:85], 0
	v_mov_b64_e32 v[86:87], 0
	v_mov_b64_e32 v[88:89], 0
	v_mov_b64_e32 v[90:91], 0
	v_mov_b64_e32 v[92:93], 0
	v_mov_b64_e32 v[94:95], 0
	v_mov_b64_e32 v[96:97], 0
	v_mov_b64_e32 v[98:99], 0
	v_mov_b64_e32 v[100:101], 0
	v_mov_b64_e32 v[102:103], 0
	v_mov_b64_e32 v[104:105], 0
	v_mov_b64_e32 v[106:107], 0
	v_mov_b64_e32 v[108:109], 0
	v_mov_b64_e32 v[110:111], 0
	v_mov_b64_e32 v[112:113], 0
	v_mov_b64_e32 v[114:115], 0
	v_mov_b64_e32 v[116:117], 0
	v_mov_b64_e32 v[118:119], 0
	v_mov_b64_e32 v[120:121], 0
	v_mov_b64_e32 v[122:123], 0
	v_mov_b64_e32 v[124:125], 0
	v_mov_b64_e32 v[126:127], 0

.LBB0_996:
	s_ashr_i32 s41, s40, 31
	v_cmp_lt_i64_e32 vcc, s[44:45], v[148:149]
	s_lshl_b64 s[44:45], s[40:41], 18
	s_add_u32 s44, s74, s44
	s_addc_u32 s45, s75, s45
	s_and_b64 s[46:47], vcc, exec
	s_cselect_b32 s9, s45, s49
	s_cselect_b32 s41, s44, s48
	s_ashr_i32 s39, s38, 31
	s_lshl_b64 s[46:47], s[38:39], 18
	s_add_u32 s46, s72, s46
	s_addc_u32 s47, s73, s47
	s_and_b64 s[52:53], vcc, exec
	s_cselect_b32 s39, s47, s51
	s_cselect_b32 s76, s46, s50
	s_add_u32 s48, s48, 0x20080
	s_addc_u32 s49, s49, 0
	s_add_u32 s77, s50, 0x100
	v_mov_b32_e32 v0, 0
	s_addc_u32 s78, s51, 0
	s_mov_b32 s79, -2
	s_waitcnt lgkmcnt(0)
	v_mov_b64_e32 v[0:1], 0
	v_mov_b64_e32 v[2:3], 0
	v_mov_b64_e32 v[4:5], 0
	v_mov_b64_e32 v[6:7], 0
	v_mov_b64_e32 v[8:9], 0
	v_mov_b64_e32 v[10:11], 0
	v_mov_b64_e32 v[12:13], 0
	v_mov_b64_e32 v[14:15], 0
	v_mov_b64_e32 v[16:17], 0
	v_mov_b64_e32 v[18:19], 0
	v_mov_b64_e32 v[20:21], 0
	v_mov_b64_e32 v[22:23], 0
	v_mov_b64_e32 v[24:25], 0
	v_mov_b64_e32 v[26:27], 0
	v_mov_b64_e32 v[28:29], 0
	v_mov_b64_e32 v[30:31], 0
	v_mov_b64_e32 v[32:33], 0
	v_mov_b64_e32 v[34:35], 0
	v_mov_b64_e32 v[36:37], 0
	v_mov_b64_e32 v[38:39], 0
	v_mov_b64_e32 v[40:41], 0
	v_mov_b64_e32 v[42:43], 0
	v_mov_b64_e32 v[44:45], 0
	v_mov_b64_e32 v[46:47], 0
	v_mov_b64_e32 v[48:49], 0
	v_mov_b64_e32 v[50:51], 0
	v_mov_b64_e32 v[52:53], 0
	v_mov_b64_e32 v[54:55], 0
	v_mov_b64_e32 v[56:57], 0
	v_mov_b64_e32 v[58:59], 0
	v_mov_b64_e32 v[60:61], 0
	v_mov_b64_e32 v[62:63], 0
	v_mov_b64_e32 v[64:65], 0
	v_mov_b64_e32 v[66:67], 0
	v_mov_b64_e32 v[68:69], 0
	v_mov_b64_e32 v[70:71], 0
	v_mov_b64_e32 v[72:73], 0
	v_mov_b64_e32 v[74:75], 0
	v_mov_b64_e32 v[76:77], 0
	v_mov_b64_e32 v[78:79], 0
	v_mov_b64_e32 v[80:81], 0
	v_mov_b64_e32 v[82:83], 0
	v_mov_b64_e32 v[84:85], 0
	v_mov_b64_e32 v[86:87], 0
	v_mov_b64_e32 v[88:89], 0
	v_mov_b64_e32 v[90:91], 0
	v_mov_b64_e32 v[92:93], 0
	v_mov_b64_e32 v[94:95], 0
	v_mov_b64_e32 v[96:97], 0
	v_mov_b64_e32 v[98:99], 0
	v_mov_b64_e32 v[100:101], 0
	v_mov_b64_e32 v[102:103], 0
	v_mov_b64_e32 v[104:105], 0
	v_mov_b64_e32 v[106:107], 0
	v_mov_b64_e32 v[108:109], 0
	v_mov_b64_e32 v[110:111], 0
	v_mov_b64_e32 v[112:113], 0
	v_mov_b64_e32 v[114:115], 0
	v_mov_b64_e32 v[116:117], 0
	v_mov_b64_e32 v[118:119], 0
	v_mov_b64_e32 v[120:121], 0
	v_mov_b64_e32 v[122:123], 0
	v_mov_b64_e32 v[124:125], 0
	v_mov_b64_e32 v[126:127], 0

.LBB0_1092:
	s_ashr_i32 s37, s36, 31
	v_cmp_lt_i64_e32 vcc, s[0:1], v[142:143]
	s_lshl_b64 s[0:1], s[36:37], 19
	s_add_u32 s38, s68, s0
	s_addc_u32 s39, s69, s1
	s_and_b64 s[0:1], vcc, exec
	s_cselect_b32 s37, s39, s45
	s_cselect_b32 s60, s38, s44
	s_ashr_i32 s13, s12, 31
	s_lshl_b64 s[0:1], s[12:13], 19
	s_add_u32 s40, s70, s0
	s_addc_u32 s41, s71, s1
	s_and_b64 s[0:1], vcc, exec
	s_cselect_b32 s13, s41, s43
	s_cselect_b32 s61, s40, s42
	s_add_u32 s0, s44, 0x40080
	s_addc_u32 s1, s45, 0
	s_add_u32 s62, s42, 0x100
	v_mov_b32_e32 v0, 0
	s_addc_u32 s63, s43, 0
	s_mov_b32 s64, -2
	v_mov_b64_e32 v[0:1], 0
	v_mov_b64_e32 v[2:3], 0
	v_mov_b64_e32 v[4:5], 0
	v_mov_b64_e32 v[6:7], 0
	v_mov_b64_e32 v[8:9], 0
	v_mov_b64_e32 v[10:11], 0
	v_mov_b64_e32 v[12:13], 0
	v_mov_b64_e32 v[14:15], 0
	v_mov_b64_e32 v[16:17], 0
	v_mov_b64_e32 v[18:19], 0
	v_mov_b64_e32 v[20:21], 0
	v_mov_b64_e32 v[22:23], 0
	v_mov_b64_e32 v[24:25], 0
	v_mov_b64_e32 v[26:27], 0
	v_mov_b64_e32 v[28:29], 0
	v_mov_b64_e32 v[30:31], 0
	v_mov_b64_e32 v[32:33], 0
	v_mov_b64_e32 v[34:35], 0
	v_mov_b64_e32 v[36:37], 0
	v_mov_b64_e32 v[38:39], 0
	v_mov_b64_e32 v[40:41], 0
	v_mov_b64_e32 v[42:43], 0
	v_mov_b64_e32 v[44:45], 0
	v_mov_b64_e32 v[46:47], 0
	v_mov_b64_e32 v[48:49], 0
	v_mov_b64_e32 v[50:51], 0
	v_mov_b64_e32 v[52:53], 0
	v_mov_b64_e32 v[54:55], 0
	v_mov_b64_e32 v[56:57], 0
	v_mov_b64_e32 v[58:59], 0
	v_mov_b64_e32 v[60:61], 0
	v_mov_b64_e32 v[62:63], 0
	v_mov_b64_e32 v[64:65], 0
	v_mov_b64_e32 v[66:67], 0
	v_mov_b64_e32 v[68:69], 0
	v_mov_b64_e32 v[70:71], 0
	v_mov_b64_e32 v[72:73], 0
	v_mov_b64_e32 v[74:75], 0
	v_mov_b64_e32 v[76:77], 0
	v_mov_b64_e32 v[78:79], 0
	v_mov_b64_e32 v[80:81], 0
	v_mov_b64_e32 v[82:83], 0
	v_mov_b64_e32 v[84:85], 0
	v_mov_b64_e32 v[86:87], 0
	v_mov_b64_e32 v[88:89], 0
	v_mov_b64_e32 v[90:91], 0
	v_mov_b64_e32 v[92:93], 0
	v_mov_b64_e32 v[94:95], 0
	v_mov_b64_e32 v[96:97], 0
	v_mov_b64_e32 v[98:99], 0
	v_mov_b64_e32 v[100:101], 0
	v_mov_b64_e32 v[102:103], 0
	v_mov_b64_e32 v[104:105], 0
	v_mov_b64_e32 v[106:107], 0
	v_mov_b64_e32 v[108:109], 0
	v_mov_b64_e32 v[110:111], 0
	v_mov_b64_e32 v[112:113], 0
	v_mov_b64_e32 v[114:115], 0
	v_mov_b64_e32 v[116:117], 0
	v_mov_b64_e32 v[118:119], 0
	v_mov_b64_e32 v[120:121], 0
	v_mov_b64_e32 v[122:123], 0
	v_mov_b64_e32 v[124:125], 0
	v_mov_b64_e32 v[126:127], 0

.LBB0_1168:
	s_add_u32 s63, s42, 0x100
	v_mov_b32_e32 v0, 0
	s_addc_u32 s64, s43, 0
	s_mov_b32 s65, -2
	s_waitcnt lgkmcnt(0)
	v_mov_b64_e32 v[0:1], 0
	v_mov_b64_e32 v[2:3], 0
	v_mov_b64_e32 v[4:5], 0
	v_mov_b64_e32 v[6:7], 0
	v_mov_b64_e32 v[8:9], 0
	v_mov_b64_e32 v[10:11], 0
	v_mov_b64_e32 v[12:13], 0
	v_mov_b64_e32 v[14:15], 0
	v_mov_b64_e32 v[16:17], 0
	v_mov_b64_e32 v[18:19], 0
	v_mov_b64_e32 v[20:21], 0
	v_mov_b64_e32 v[22:23], 0
	v_mov_b64_e32 v[24:25], 0
	v_mov_b64_e32 v[26:27], 0
	v_mov_b64_e32 v[28:29], 0
	v_mov_b64_e32 v[30:31], 0
	v_mov_b64_e32 v[32:33], 0
	v_mov_b64_e32 v[34:35], 0
	v_mov_b64_e32 v[36:37], 0
	v_mov_b64_e32 v[38:39], 0
	v_mov_b64_e32 v[40:41], 0
	v_mov_b64_e32 v[42:43], 0
	v_mov_b64_e32 v[44:45], 0
	v_mov_b64_e32 v[46:47], 0
	v_mov_b64_e32 v[48:49], 0
	v_mov_b64_e32 v[50:51], 0
	v_mov_b64_e32 v[52:53], 0
	v_mov_b64_e32 v[54:55], 0
	v_mov_b64_e32 v[56:57], 0
	v_mov_b64_e32 v[58:59], 0
	v_mov_b64_e32 v[60:61], 0
	v_mov_b64_e32 v[62:63], 0
	v_mov_b64_e32 v[64:65], 0
	v_mov_b64_e32 v[66:67], 0
	v_mov_b64_e32 v[68:69], 0
	v_mov_b64_e32 v[70:71], 0
	v_mov_b64_e32 v[72:73], 0
	v_mov_b64_e32 v[74:75], 0
	v_mov_b64_e32 v[76:77], 0
	v_mov_b64_e32 v[78:79], 0
	v_mov_b64_e32 v[80:81], 0
	v_mov_b64_e32 v[82:83], 0
	v_mov_b64_e32 v[84:85], 0
	v_mov_b64_e32 v[86:87], 0
	v_mov_b64_e32 v[88:89], 0
	v_mov_b64_e32 v[90:91], 0
	v_mov_b64_e32 v[92:93], 0
	v_mov_b64_e32 v[94:95], 0
	v_mov_b64_e32 v[96:97], 0
	v_mov_b64_e32 v[98:99], 0
	v_mov_b64_e32 v[100:101], 0
	v_mov_b64_e32 v[102:103], 0
	v_mov_b64_e32 v[104:105], 0
	v_mov_b64_e32 v[106:107], 0
	v_mov_b64_e32 v[108:109], 0
	v_mov_b64_e32 v[110:111], 0
	v_mov_b64_e32 v[112:113], 0
	v_mov_b64_e32 v[114:115], 0
	v_mov_b64_e32 v[116:117], 0
	v_mov_b64_e32 v[118:119], 0
	v_mov_b64_e32 v[120:121], 0
	v_mov_b64_e32 v[122:123], 0
	v_mov_b64_e32 v[124:125], 0
	v_mov_b64_e32 v[126:127], 0
